# strategy 8 MFMA-LDS interleave in the mixer: v054 + the SGU kk=2/kk=3 MFMA blocks keep four ds_read_b128 in flight (counted lgkmcnt) instead of one read + lgkmcnt(0) per MFMA
# speedup vs baseline: 1.0002x; 1.0002x over previous
.LBB0_766:
	v_lshl_add_u64 v[18:19], v[68:69], 0, s[8:9]
	global_load_dword v58, v[18:19], off
	v_lshl_add_u64 v[18:19], s[56:57], 0, v[130:131]
	v_add_co_u32_e32 v18, vcc, 0x32000000, v18
	v_add_u32_e32 v30, s6, v84
	s_nop 0
	v_addc_co_u32_e32 v19, vcc, 0, v19, vcc
	global_load_dwordx2 v[146:147], v[18:19], off nt
	global_load_dwordx2 v[144:145], v[18:19], off offset:32 nt
	global_load_dwordx2 v[142:143], v[18:19], off offset:64 nt
	global_load_dwordx2 v[140:141], v[18:19], off offset:96 nt
	global_load_dwordx2 v[138:139], v[18:19], off offset:128 nt
	global_load_dwordx2 v[64:65], v[18:19], off offset:160 nt
	global_load_dwordx2 v[62:63], v[18:19], off offset:192 nt
	global_load_dwordx2 v[60:61], v[18:19], off offset:224 nt
	v_lshl_add_u64 v[18:19], s[56:57], 0, v[72:73]
	v_add_co_u32_e32 v22, vcc, 0xcd00000, v18
	v_add_u32_e32 v59, v30, v227
	s_nop 0
	v_addc_co_u32_e32 v23, vcc, 0, v19, vcc
	global_load_dwordx4 v[26:29], v[22:23], off
	global_load_dwordx4 v[18:21], v[22:23], off offset:64
	global_load_dwordx4 v[42:45], v[22:23], off offset:128
	s_nop 0
	global_load_dwordx4 v[22:25], v[22:23], off offset:192
	s_waitcnt lgkmcnt(0)
	s_waitcnt lgkmcnt(0)
	s_barrier
	ds_read_b128 v[38:41], v59 offset:9728
	ds_read_b128 v[46:49], v59 offset:14080
	ds_read_b128 v[30:33], v59 offset:1024
	ds_read_b128 v[34:37], v59 offset:5376
	v_cndmask_b32_e64 v127, 0, 1, s[62:63]
	v_cmp_ne_u32_e64 s[6:7], 1, v127
	s_andn2_b64 vcc, exec, s[62:63]
	s_waitcnt vmcnt(3) lgkmcnt(2)
	v_mfma_f32_16x16x32_bf16 v[148:151], v[46:49], v[26:29], 0
	ds_read_b128 v[46:49], v59 offset:18432
	s_waitcnt lgkmcnt(0)
	v_mfma_f32_16x16x32_bf16 v[152:155], v[46:49], v[26:29], 0
	ds_read_b128 v[46:49], v59 offset:22784
	s_waitcnt lgkmcnt(0)
	v_mfma_f32_16x16x32_bf16 v[156:159], v[46:49], v[26:29], 0
	ds_read_b128 v[46:49], v59 offset:27136
	s_waitcnt lgkmcnt(0)
	v_mfma_f32_16x16x32_bf16 v[172:175], v[46:49], v[26:29], 0
	ds_read_b128 v[46:49], v59 offset:31488
	v_mfma_f32_16x16x32_bf16 v[30:33], v[30:33], v[26:29], 0
	v_mfma_f32_16x16x32_bf16 v[34:37], v[34:37], v[26:29], 0
	v_mfma_f32_16x16x32_bf16 v[38:41], v[38:41], v[26:29], 0
	s_waitcnt lgkmcnt(0)
	v_mfma_f32_16x16x32_bf16 v[176:179], v[46:49], v[26:29], 0
	ds_read_b128 v[26:29], v59 offset:1088
	s_waitcnt vmcnt(2) lgkmcnt(0)
	v_mfma_f32_16x16x32_bf16 v[54:57], v[26:29], v[18:21], v[30:33]
	ds_read_b128 v[26:29], v59 offset:5440
	s_waitcnt lgkmcnt(0)
	v_mfma_f32_16x16x32_bf16 v[50:53], v[26:29], v[18:21], v[34:37]
	ds_read_b128 v[26:29], v59 offset:9792
	s_waitcnt lgkmcnt(0)
	v_mfma_f32_16x16x32_bf16 v[46:49], v[26:29], v[18:21], v[38:41]
	ds_read_b128 v[26:29], v59 offset:14144
	s_waitcnt lgkmcnt(0)
	v_mfma_f32_16x16x32_bf16 v[38:41], v[26:29], v[18:21], v[148:151]
	ds_read_b128 v[26:29], v59 offset:18496
	s_nop 1
	ds_read_b128 v[148:151], v59 offset:31552
	s_waitcnt lgkmcnt(1)
	v_mfma_f32_16x16x32_bf16 v[34:37], v[26:29], v[18:21], v[152:155]
	ds_read_b128 v[26:29], v59 offset:22848
	s_waitcnt lgkmcnt(0)
	v_mfma_f32_16x16x32_bf16 v[30:33], v[26:29], v[18:21], v[156:159]
	ds_read_b128 v[26:29], v59 offset:27200
	s_waitcnt lgkmcnt(0)
	v_mfma_f32_16x16x32_bf16 v[26:29], v[26:29], v[18:21], v[172:175]
	v_mfma_f32_16x16x32_bf16 v[18:21], v[148:151], v[18:21], v[176:179]
	s_cbranch_vccnz .LBB0_768
	ds_read_b128 v[148:151], v59 offset:1152
	ds_read_b128 v[180:183], v59 offset:5504
	ds_read_b128 v[184:187], v59 offset:9856
	ds_read_b128 v[188:191], v59 offset:14208
	s_waitcnt vmcnt(1) lgkmcnt(3)
	v_mfma_f32_16x16x32_bf16 v[54:57], v[148:151], v[42:45], v[54:57]
	ds_read_b128 v[148:151], v59 offset:18560
	s_waitcnt lgkmcnt(3)
	v_mfma_f32_16x16x32_bf16 v[50:53], v[180:183], v[42:45], v[50:53]
	ds_read_b128 v[180:183], v59 offset:22912
	s_waitcnt lgkmcnt(3)
	v_mfma_f32_16x16x32_bf16 v[46:49], v[184:187], v[42:45], v[46:49]
	ds_read_b128 v[184:187], v59 offset:27264
	s_waitcnt lgkmcnt(3)
	v_mfma_f32_16x16x32_bf16 v[38:41], v[188:191], v[42:45], v[38:41]
	ds_read_b128 v[188:191], v59 offset:31616
	s_waitcnt lgkmcnt(3)
	v_mfma_f32_16x16x32_bf16 v[34:37], v[148:151], v[42:45], v[34:37]
	s_waitcnt lgkmcnt(2)
	v_mfma_f32_16x16x32_bf16 v[30:33], v[180:183], v[42:45], v[30:33]
	s_waitcnt lgkmcnt(1)
	v_mfma_f32_16x16x32_bf16 v[26:29], v[184:187], v[42:45], v[26:29]
	s_waitcnt lgkmcnt(0)
	v_mfma_f32_16x16x32_bf16 v[18:21], v[188:191], v[42:45], v[18:21]
.LBB0_768:
	s_and_b64 vcc, exec, s[6:7]
	s_cbranch_vccnz .LBB0_763
	s_waitcnt vmcnt(1)
	ds_read_b128 v[42:45], v59 offset:1216
	ds_read_b128 v[180:183], v59 offset:5568
	ds_read_b128 v[184:187], v59 offset:9920
	ds_read_b128 v[188:191], v59 offset:14272
	s_waitcnt vmcnt(0) lgkmcnt(3)
	v_mfma_f32_16x16x32_bf16 v[54:57], v[42:45], v[22:25], v[54:57]
	ds_read_b128 v[42:45], v59 offset:18624
	s_waitcnt lgkmcnt(3)
	v_mfma_f32_16x16x32_bf16 v[50:53], v[180:183], v[22:25], v[50:53]
	ds_read_b128 v[180:183], v59 offset:22976
	s_waitcnt lgkmcnt(3)
	v_mfma_f32_16x16x32_bf16 v[46:49], v[184:187], v[22:25], v[46:49]
	ds_read_b128 v[184:187], v59 offset:27328
	s_waitcnt lgkmcnt(3)
	v_mfma_f32_16x16x32_bf16 v[38:41], v[188:191], v[22:25], v[38:41]
	ds_read_b128 v[188:191], v59 offset:31680
	s_waitcnt lgkmcnt(3)
	v_mfma_f32_16x16x32_bf16 v[34:37], v[42:45], v[22:25], v[34:37]
	s_waitcnt lgkmcnt(2)
	v_mfma_f32_16x16x32_bf16 v[30:33], v[180:183], v[22:25], v[30:33]
	s_waitcnt lgkmcnt(1)
	v_mfma_f32_16x16x32_bf16 v[26:29], v[184:187], v[22:25], v[26:29]
	s_waitcnt lgkmcnt(0)
	v_mfma_f32_16x16x32_bf16 v[18:21], v[188:191], v[22:25], v[18:21]
	s_branch .LBB0_763
